# code placement: P6 RMSNorm loop region shifted by 4 bytes (one s_nop before and after the region); instruction stream otherwise identical to the previous version
# speedup vs baseline: 1.0022x; 1.0022x over previous
.LBB0_1209:
	s_or_b64 exec, exec, s[4:5]
	s_waitcnt lgkmcnt(0)
	s_barrier
	s_nop 0

.LBB0_1225:
	global_store_dwordx2 v[78:79], v[0:1], off offset:3584
	s_branch .LBB0_1213
	s_nop 0
